# two-block barrier intervals with waves 4-7 starting each interval 384 cycles later (SIMD partners out of phase)
# baseline (speedup 1.0000x reference)
; template <int MODE> ...
;     ...
;     for (int jA = j0, pp = 0; jA <= qb; jA += 2, pp ^= 1) {
;       for (int sub = 0; sub < 2; ++sub) {
;         const int j = jA + sub; if (j > qb) break;
;         const bool pre = j + 2 <= qb;
;         if (pre) NSA_LD1(j + 2);
;         const LAS bf16_t* Ks = stage + pp * 18432 + sub * 9216; const LAS bf16_t* Vs = Ks + 4608;
;         const bool far = MODE == 0 && (qb - j >= 17);
; #pragma unroll
;         for (int tile = 0; tile < 2; ++tile) {
;             const int tl0 = wave * 8 + tile * 4, t0 = qb * 64 + tl0;
;             unsigned mb[4] = {1u, 1u, 1u, 1u};
;             if (MODE == 0) {
; #pragma unroll
;                 for (int i = 0; i < 4; ++i) mb[i] = (masks[(tl0 + i) * 4 + (j >> 5)] >> (j & 31)) & 1u; }
;             if (MODE == 1 || __builtin_amdgcn_readfirstlane((int)(mb[0] | mb[1] | mb[2] | mb[3]))) {
;                 f32x4 sc[4];
; #pragma unroll
;                 for (int cc = 0; cc < 4; ++cc) { const LAS bf16_t* kp = Ks + (cc * 16 + r16) * 72 + q4 * 8;
;                     sc[cc] = MFMA16(aq[tile][0], *(const LAS bf16x8*)kp, z4); sc[cc] = MFMA16(aq[tile][1], *(const LAS bf16x8*)(kp + 32), sc[cc]); }
;                 if (far) {
; #pragma unroll
;                     for (int cc = 0; cc < 4; ++cc)
; #pragma unroll
;                         for (int i = 0; i < 4; ++i) { const float p = mb[i] ? ex2(sc[cc][i] + bfar) : 0.f; ls[tile][i] += p; Pb[(4 * q4 + i) * 72 + cc * 16 + r16] = tobf(p); }
;                 } else {
; #pragma unroll
;                     for (int cc = 0; cc < 4; ++cc) { const int pos = j * 64 + cc * 16 + r16;
; #pragma unroll
;                         for (int i = 0; i < 4; ++i) { const int dist = t0 + i - pos; const bool ok = MODE ? ((unsigned)dist < 512u) : (dist >= 0 && mb[i]);
;                             const float p = ok ? ex2(sc[cc][i] + bt[clampd(dist)]) : 0.f; ls[tile][i] += p; Pb[(4 * q4 + i) * 72 + cc * 16 + r16] = tobf(p); } }
;                 }
;                 CBAR();
; #pragma unroll
;                 for (int ks = 0; ks < 2; ++ks) { const bf16x8 aP = *(const LAS bf16x8*)(Pb + r16 * 72 + ks * 32 + q4 * 8);
; #pragma unroll
;                     for (int nt = 0; nt < 4; ++nt) os[tile][nt] = MFMA16(aP, *(const LAS bf16x8*)(Vs + (nt * 16 + r16) * 72 + ks * 32 + q4 * 8), os[tile][nt]); }
;                 CBAR();
;             }
;         }
.Lnsa_pbar_27:
	s_waitcnt vmcnt(0) lgkmcnt(0)
	s_barrier
	s_cmp_lt_u32 s80, 32
	s_cbranch_scc1 .Lnsa_nostag_29
	s_sleep 6
.Lnsa_nostag_29:
.Lnsa_pnobar_28:
	s_mov_b32 s93, s94
	s_mov_b32 s94, s95
	s_mov_b32 s95, s74
	s_add_i32 s57, s57, 1
	s_cmp_lt_u32 s57, s92
	s_cbranch_scc1 .Lnsa_blk_loop
	s_cmp_lg_u32 s54, 0
	s_cbranch_scc1 .Lnsa_noearly_30
	s_add_u32 s66, s30, 0x35900000
	s_addc_u32 s67, s31, 0
	s_add_u32 s68, s30, 0x36900000
	s_addc_u32 s69, s31, 0
	s_lshr_b32 s15, s97, 13
	s_lshl_b32 s15, s15, 2
	s_and_b32 s1, s88, 3
	s_or_b32 s15, s15, s1
	s_lshl_b32 s15, s15, 20
	s_add_u32 s66, s66, s15
	s_addc_u32 s67, s67, 0
	s_add_u32 s68, s68, s15
	s_addc_u32 s69, s69, 0
	s_lshl_b32 s33, s80, 7
	s_add_i32 s33, s33, 56384
	s_add_i32 s14, s18, -8
	s_max_i32 s14, s14, 0
	s_mov_b32 s15, 0
	s_and_b32 s0, s15, 3
	s_lshl_b32 s0, s0, 14
	s_add_i32 s0, s0, s33
	s_lshl_b32 s1, s14, 13
	s_add_u32 s70, s66, s1
	s_addc_u32 s71, s67, 0
	s_mov_b32 m0, s0
	s_lshl_b32 s1, s14, 7
	global_load_lds_dwordx4 v174, s[70:71]
	s_add_u32 s70, s68, s1
	s_addc_u32 s71, s69, 0
	s_add_i32 m0, s0, 8192
	s_add_i32 s1, s15, 0
	global_load_lds_dwordx4 v175, s[70:71]
	s_add_i32 s14, s14, 1
	s_min_i32 s14, s14, s18
	s_mov_b32 s15, 1
	s_and_b32 s0, s15, 3
	s_lshl_b32 s0, s0, 14
	s_add_i32 s0, s0, s33
	s_lshl_b32 s1, s14, 13
	s_add_u32 s70, s66, s1
	s_addc_u32 s71, s67, 0
	s_mov_b32 m0, s0
	s_lshl_b32 s1, s14, 7
	global_load_lds_dwordx4 v174, s[70:71]
	s_add_u32 s70, s68, s1
	s_addc_u32 s71, s69, 0
	s_add_i32 m0, s0, 8192
	s_add_i32 s1, s15, 0
	global_load_lds_dwordx4 v175, s[70:71]
